# SwiGLU epilogue: the two accumulator groups of each store chunk software-pipelined (no hazard nops, transcendental latency covered)
# speedup vs baseline: 1.0030x; 1.0030x over previous
.LBB0_801:
	v_mov_b32_e32 v204, 0xbfb8aa3b
	v_pk_mul_f32 v[200:201], v[116:117], v[204:205] op_sel_hi:[1,0]
	v_pk_mul_f32 v[202:203], v[118:119], v[204:205] op_sel_hi:[1,0]
	v_pk_mul_f32 v[206:207], v[124:125], v[204:205] op_sel_hi:[1,0]
	v_pk_mul_f32 v[208:209], v[126:127], v[204:205] op_sel_hi:[1,0]
	v_exp_f32_e32 v200, v200
	v_exp_f32_e32 v201, v201
	v_exp_f32_e32 v202, v202
	v_exp_f32_e32 v203, v203
	v_pk_mul_f32 v[112:113], v[116:117], v[112:113]
	v_pk_mul_f32 v[114:115], v[118:119], v[114:115]
	v_exp_f32_e32 v206, v206
	v_exp_f32_e32 v207, v207
	v_exp_f32_e32 v208, v208
	v_exp_f32_e32 v209, v209
	v_pk_mul_f32 v[120:121], v[124:125], v[120:121]
	v_pk_mul_f32 v[122:123], v[126:127], v[122:123]
	v_pk_add_f32 v[200:201], v[200:201], 1.0 op_sel_hi:[1,0]
	v_pk_add_f32 v[202:203], v[202:203], 1.0 op_sel_hi:[1,0]
	v_rcp_f32_e32 v200, v200
	v_rcp_f32_e32 v201, v201
	v_rcp_f32_e32 v202, v202
	v_rcp_f32_e32 v203, v203
	v_pk_add_f32 v[206:207], v[206:207], 1.0 op_sel_hi:[1,0]
	v_pk_add_f32 v[208:209], v[208:209], 1.0 op_sel_hi:[1,0]
	v_rcp_f32_e32 v206, v206
	v_rcp_f32_e32 v207, v207
	v_rcp_f32_e32 v208, v208
	v_rcp_f32_e32 v209, v209
	v_pk_mul_f32 v[112:113], v[200:201], v[112:113]
	v_pk_mul_f32 v[114:115], v[202:203], v[114:115]
	v_pk_mul_f32 v[120:121], v[206:207], v[120:121]
	v_pk_mul_f32 v[122:123], v[208:209], v[122:123]
	v_cvt_pk_bf16_f32 v124, v120, v121
	v_cvt_pk_bf16_f32 v125, v122, v123
	v_cvt_pk_bf16_f32 v126, v112, v113
	v_cvt_pk_bf16_f32 v127, v114, v115
	v_lshl_or_b32 v158, s57, 7, v150
	v_lshl_add_u32 v156, s24, 8, v148
	v_ashrrev_i32_e32 v159, 31, v158
	v_mov_b64_e32 v[112:113], s[8:9]
	v_mad_i64_i32 v[120:121], s[26:27], v156, s56, v[112:113]
	v_lshlrev_b64 v[114:115], 1, v[158:159]
	v_lshl_add_u64 v[120:121], v[120:121], 0, v[114:115]
	global_store_dwordx4 v[120:121], v[124:127], off
	v_pk_mul_f32 v[200:201], v[100:101], v[204:205] op_sel_hi:[1,0]
	v_pk_mul_f32 v[202:203], v[102:103], v[204:205] op_sel_hi:[1,0]
	v_pk_mul_f32 v[206:207], v[108:109], v[204:205] op_sel_hi:[1,0]
	v_pk_mul_f32 v[208:209], v[110:111], v[204:205] op_sel_hi:[1,0]
	v_exp_f32_e32 v200, v200
	v_exp_f32_e32 v201, v201
	v_exp_f32_e32 v202, v202
	v_exp_f32_e32 v203, v203
	v_pk_mul_f32 v[96:97], v[100:101], v[96:97]
	v_pk_mul_f32 v[98:99], v[102:103], v[98:99]
	v_exp_f32_e32 v206, v206
	v_exp_f32_e32 v207, v207
	v_exp_f32_e32 v208, v208
	v_exp_f32_e32 v209, v209
	v_pk_mul_f32 v[104:105], v[108:109], v[104:105]
	v_pk_mul_f32 v[106:107], v[110:111], v[106:107]
	v_pk_add_f32 v[200:201], v[200:201], 1.0 op_sel_hi:[1,0]
	v_pk_add_f32 v[202:203], v[202:203], 1.0 op_sel_hi:[1,0]
	v_rcp_f32_e32 v200, v200
	v_rcp_f32_e32 v201, v201
	v_rcp_f32_e32 v202, v202
	v_rcp_f32_e32 v203, v203
	v_pk_add_f32 v[206:207], v[206:207], 1.0 op_sel_hi:[1,0]
	v_pk_add_f32 v[208:209], v[208:209], 1.0 op_sel_hi:[1,0]
	v_rcp_f32_e32 v206, v206
	v_rcp_f32_e32 v207, v207
	v_rcp_f32_e32 v208, v208
	v_rcp_f32_e32 v209, v209
	v_pk_mul_f32 v[96:97], v[200:201], v[96:97]
	v_pk_mul_f32 v[98:99], v[202:203], v[98:99]
	v_pk_mul_f32 v[104:105], v[206:207], v[104:105]
	v_pk_mul_f32 v[106:107], v[208:209], v[106:107]
	v_cvt_pk_bf16_f32 v108, v104, v105
	v_cvt_pk_bf16_f32 v109, v106, v107
	v_cvt_pk_bf16_f32 v110, v96, v97
	v_cvt_pk_bf16_f32 v111, v98, v99
	v_or_b32_e32 v100, 16, v156
	v_mad_i64_i32 v[100:101], s[26:27], v100, s56, v[112:113]
	v_lshl_add_u64 v[100:101], v[100:101], 0, v[114:115]
	global_store_dwordx4 v[100:101], v[108:111], off
	v_pk_mul_f32 v[200:201], v[84:85], v[204:205] op_sel_hi:[1,0]
	v_pk_mul_f32 v[202:203], v[86:87], v[204:205] op_sel_hi:[1,0]
	v_pk_mul_f32 v[206:207], v[92:93], v[204:205] op_sel_hi:[1,0]
	v_pk_mul_f32 v[208:209], v[94:95], v[204:205] op_sel_hi:[1,0]
	v_exp_f32_e32 v200, v200
	v_exp_f32_e32 v201, v201
	v_exp_f32_e32 v202, v202
	v_exp_f32_e32 v203, v203
	v_pk_mul_f32 v[80:81], v[84:85], v[80:81]
	v_pk_mul_f32 v[82:83], v[86:87], v[82:83]
	v_exp_f32_e32 v206, v206
	v_exp_f32_e32 v207, v207
	v_exp_f32_e32 v208, v208
	v_exp_f32_e32 v209, v209
	v_pk_mul_f32 v[88:89], v[92:93], v[88:89]
	v_pk_mul_f32 v[90:91], v[94:95], v[90:91]
	v_pk_add_f32 v[200:201], v[200:201], 1.0 op_sel_hi:[1,0]
	v_pk_add_f32 v[202:203], v[202:203], 1.0 op_sel_hi:[1,0]
	v_rcp_f32_e32 v200, v200
	v_rcp_f32_e32 v201, v201
	v_rcp_f32_e32 v202, v202
	v_rcp_f32_e32 v203, v203
	v_pk_add_f32 v[206:207], v[206:207], 1.0 op_sel_hi:[1,0]
	v_pk_add_f32 v[208:209], v[208:209], 1.0 op_sel_hi:[1,0]
	v_rcp_f32_e32 v206, v206
	v_rcp_f32_e32 v207, v207
	v_rcp_f32_e32 v208, v208
	v_rcp_f32_e32 v209, v209
	v_pk_mul_f32 v[80:81], v[200:201], v[80:81]
	v_pk_mul_f32 v[82:83], v[202:203], v[82:83]
	v_pk_mul_f32 v[88:89], v[206:207], v[88:89]
	v_pk_mul_f32 v[90:91], v[208:209], v[90:91]
	v_cvt_pk_bf16_f32 v92, v88, v89
	v_cvt_pk_bf16_f32 v93, v90, v91
	v_cvt_pk_bf16_f32 v94, v80, v81
	v_cvt_pk_bf16_f32 v95, v82, v83
	v_or_b32_e32 v84, 32, v156
	v_mad_i64_i32 v[84:85], s[26:27], v84, s56, v[112:113]
	v_lshl_add_u64 v[84:85], v[84:85], 0, v[114:115]
	global_store_dwordx4 v[84:85], v[92:95], off
	v_pk_mul_f32 v[200:201], v[68:69], v[204:205] op_sel_hi:[1,0]
	v_pk_mul_f32 v[202:203], v[70:71], v[204:205] op_sel_hi:[1,0]
	v_pk_mul_f32 v[206:207], v[76:77], v[204:205] op_sel_hi:[1,0]
	v_pk_mul_f32 v[208:209], v[78:79], v[204:205] op_sel_hi:[1,0]
	v_exp_f32_e32 v200, v200
	v_exp_f32_e32 v201, v201
	v_exp_f32_e32 v202, v202
	v_exp_f32_e32 v203, v203
	v_pk_mul_f32 v[64:65], v[68:69], v[64:65]
	v_pk_mul_f32 v[66:67], v[70:71], v[66:67]
	v_exp_f32_e32 v206, v206
	v_exp_f32_e32 v207, v207
	v_exp_f32_e32 v208, v208
	v_exp_f32_e32 v209, v209
	v_pk_mul_f32 v[72:73], v[76:77], v[72:73]
	v_pk_mul_f32 v[74:75], v[78:79], v[74:75]
	v_pk_add_f32 v[200:201], v[200:201], 1.0 op_sel_hi:[1,0]
	v_pk_add_f32 v[202:203], v[202:203], 1.0 op_sel_hi:[1,0]
	v_rcp_f32_e32 v200, v200
	v_rcp_f32_e32 v201, v201
	v_rcp_f32_e32 v202, v202
	v_rcp_f32_e32 v203, v203
	v_pk_add_f32 v[206:207], v[206:207], 1.0 op_sel_hi:[1,0]
	v_pk_add_f32 v[208:209], v[208:209], 1.0 op_sel_hi:[1,0]
	v_rcp_f32_e32 v206, v206
	v_rcp_f32_e32 v207, v207
	v_rcp_f32_e32 v208, v208
	v_rcp_f32_e32 v209, v209
	v_pk_mul_f32 v[64:65], v[200:201], v[64:65]
	v_pk_mul_f32 v[66:67], v[202:203], v[66:67]
	v_pk_mul_f32 v[72:73], v[206:207], v[72:73]
	v_pk_mul_f32 v[74:75], v[208:209], v[74:75]
	v_cvt_pk_bf16_f32 v76, v72, v73
	v_cvt_pk_bf16_f32 v77, v74, v75
	v_cvt_pk_bf16_f32 v78, v64, v65
	v_cvt_pk_bf16_f32 v79, v66, v67
	v_or_b32_e32 v68, 48, v156
	v_mad_i64_i32 v[68:69], s[26:27], v68, s56, v[112:113]
	v_lshl_add_u64 v[68:69], v[68:69], 0, v[114:115]
	global_store_dwordx4 v[68:69], v[76:79], off
	v_pk_mul_f32 v[200:201], v[52:53], v[204:205] op_sel_hi:[1,0]
	v_pk_mul_f32 v[202:203], v[54:55], v[204:205] op_sel_hi:[1,0]
	v_pk_mul_f32 v[206:207], v[60:61], v[204:205] op_sel_hi:[1,0]
	v_pk_mul_f32 v[208:209], v[62:63], v[204:205] op_sel_hi:[1,0]
	v_exp_f32_e32 v200, v200
	v_exp_f32_e32 v201, v201
	v_exp_f32_e32 v202, v202
	v_exp_f32_e32 v203, v203
	v_pk_mul_f32 v[48:49], v[52:53], v[48:49]
	v_pk_mul_f32 v[50:51], v[54:55], v[50:51]
	v_exp_f32_e32 v206, v206
	v_exp_f32_e32 v207, v207
	v_exp_f32_e32 v208, v208
	v_exp_f32_e32 v209, v209
	v_pk_mul_f32 v[56:57], v[60:61], v[56:57]
	v_pk_mul_f32 v[58:59], v[62:63], v[58:59]
	v_pk_add_f32 v[200:201], v[200:201], 1.0 op_sel_hi:[1,0]
	v_pk_add_f32 v[202:203], v[202:203], 1.0 op_sel_hi:[1,0]
	v_rcp_f32_e32 v200, v200
	v_rcp_f32_e32 v201, v201
	v_rcp_f32_e32 v202, v202
	v_rcp_f32_e32 v203, v203
	v_pk_add_f32 v[206:207], v[206:207], 1.0 op_sel_hi:[1,0]
	v_pk_add_f32 v[208:209], v[208:209], 1.0 op_sel_hi:[1,0]
	v_rcp_f32_e32 v206, v206
	v_rcp_f32_e32 v207, v207
	v_rcp_f32_e32 v208, v208
	v_rcp_f32_e32 v209, v209
	v_pk_mul_f32 v[48:49], v[200:201], v[48:49]
	v_pk_mul_f32 v[50:51], v[202:203], v[50:51]
	v_pk_mul_f32 v[56:57], v[206:207], v[56:57]
	v_pk_mul_f32 v[58:59], v[208:209], v[58:59]
	v_cvt_pk_bf16_f32 v60, v56, v57
	v_cvt_pk_bf16_f32 v61, v58, v59
	v_cvt_pk_bf16_f32 v62, v48, v49
	v_cvt_pk_bf16_f32 v63, v50, v51
	v_add_u32_e32 v66, 0x80, v156
	v_mad_i64_i32 v[52:53], s[26:27], v66, s56, v[112:113]
	v_lshl_add_u64 v[52:53], v[52:53], 0, v[114:115]
	global_store_dwordx4 v[52:53], v[60:63], off
	v_pk_mul_f32 v[200:201], v[36:37], v[204:205] op_sel_hi:[1,0]
	v_pk_mul_f32 v[202:203], v[38:39], v[204:205] op_sel_hi:[1,0]
	v_pk_mul_f32 v[206:207], v[44:45], v[204:205] op_sel_hi:[1,0]
	v_pk_mul_f32 v[208:209], v[46:47], v[204:205] op_sel_hi:[1,0]
	v_exp_f32_e32 v200, v200
	v_exp_f32_e32 v201, v201
	v_exp_f32_e32 v202, v202
	v_exp_f32_e32 v203, v203
	v_pk_mul_f32 v[32:33], v[36:37], v[32:33]
	v_pk_mul_f32 v[34:35], v[38:39], v[34:35]
	v_exp_f32_e32 v206, v206
	v_exp_f32_e32 v207, v207
	v_exp_f32_e32 v208, v208
	v_exp_f32_e32 v209, v209
	v_pk_mul_f32 v[40:41], v[44:45], v[40:41]
	v_pk_mul_f32 v[42:43], v[46:47], v[42:43]
	v_pk_add_f32 v[200:201], v[200:201], 1.0 op_sel_hi:[1,0]
	v_pk_add_f32 v[202:203], v[202:203], 1.0 op_sel_hi:[1,0]
	v_rcp_f32_e32 v200, v200
	v_rcp_f32_e32 v201, v201
	v_rcp_f32_e32 v202, v202
	v_rcp_f32_e32 v203, v203
	v_pk_add_f32 v[206:207], v[206:207], 1.0 op_sel_hi:[1,0]
	v_pk_add_f32 v[208:209], v[208:209], 1.0 op_sel_hi:[1,0]
	v_rcp_f32_e32 v206, v206
	v_rcp_f32_e32 v207, v207
	v_rcp_f32_e32 v208, v208
	v_rcp_f32_e32 v209, v209
	v_pk_mul_f32 v[32:33], v[200:201], v[32:33]
	v_pk_mul_f32 v[34:35], v[202:203], v[34:35]
	v_pk_mul_f32 v[40:41], v[206:207], v[40:41]
	v_pk_mul_f32 v[42:43], v[208:209], v[42:43]
	v_cvt_pk_bf16_f32 v44, v40, v41
	v_cvt_pk_bf16_f32 v45, v42, v43
	v_cvt_pk_bf16_f32 v46, v32, v33
	v_cvt_pk_bf16_f32 v47, v34, v35
	v_add_u32_e32 v36, 0x90, v156
	v_mad_i64_i32 v[36:37], s[26:27], v36, s56, v[112:113]
	v_lshl_add_u64 v[36:37], v[36:37], 0, v[114:115]
	global_store_dwordx4 v[36:37], v[44:47], off
	v_pk_mul_f32 v[200:201], v[20:21], v[204:205] op_sel_hi:[1,0]
	v_pk_mul_f32 v[202:203], v[22:23], v[204:205] op_sel_hi:[1,0]
	v_pk_mul_f32 v[206:207], v[28:29], v[204:205] op_sel_hi:[1,0]
	v_pk_mul_f32 v[208:209], v[30:31], v[204:205] op_sel_hi:[1,0]
	v_exp_f32_e32 v200, v200
	v_exp_f32_e32 v201, v201
	v_exp_f32_e32 v202, v202
	v_exp_f32_e32 v203, v203
	v_pk_mul_f32 v[16:17], v[20:21], v[16:17]
	v_pk_mul_f32 v[18:19], v[22:23], v[18:19]
	v_exp_f32_e32 v206, v206
	v_exp_f32_e32 v207, v207
	v_exp_f32_e32 v208, v208
	v_exp_f32_e32 v209, v209
	v_pk_mul_f32 v[24:25], v[28:29], v[24:25]
	v_pk_mul_f32 v[26:27], v[30:31], v[26:27]
	v_pk_add_f32 v[200:201], v[200:201], 1.0 op_sel_hi:[1,0]
	v_pk_add_f32 v[202:203], v[202:203], 1.0 op_sel_hi:[1,0]
	v_rcp_f32_e32 v200, v200
	v_rcp_f32_e32 v201, v201
	v_rcp_f32_e32 v202, v202
	v_rcp_f32_e32 v203, v203
	v_pk_add_f32 v[206:207], v[206:207], 1.0 op_sel_hi:[1,0]
	v_pk_add_f32 v[208:209], v[208:209], 1.0 op_sel_hi:[1,0]
	v_rcp_f32_e32 v206, v206
	v_rcp_f32_e32 v207, v207
	v_rcp_f32_e32 v208, v208
	v_rcp_f32_e32 v209, v209
	v_pk_mul_f32 v[16:17], v[200:201], v[16:17]
	v_pk_mul_f32 v[18:19], v[202:203], v[18:19]
	v_pk_mul_f32 v[24:25], v[206:207], v[24:25]
	v_pk_mul_f32 v[26:27], v[208:209], v[26:27]
	v_cvt_pk_bf16_f32 v28, v24, v25
	v_cvt_pk_bf16_f32 v29, v26, v27
	v_cvt_pk_bf16_f32 v30, v16, v17
	v_cvt_pk_bf16_f32 v31, v18, v19
	v_add_u32_e32 v20, 0xa0, v156
	v_mad_i64_i32 v[20:21], s[26:27], v20, s56, v[112:113]
	v_lshl_add_u64 v[20:21], v[20:21], 0, v[114:115]
	global_store_dwordx4 v[20:21], v[28:31], off
	v_pk_mul_f32 v[200:201], v[4:5], v[204:205] op_sel_hi:[1,0]
	v_pk_mul_f32 v[202:203], v[6:7], v[204:205] op_sel_hi:[1,0]
	v_pk_mul_f32 v[206:207], v[12:13], v[204:205] op_sel_hi:[1,0]
	v_pk_mul_f32 v[208:209], v[14:15], v[204:205] op_sel_hi:[1,0]
	v_exp_f32_e32 v200, v200
	v_exp_f32_e32 v201, v201
	v_exp_f32_e32 v202, v202
	v_exp_f32_e32 v203, v203
	v_pk_mul_f32 v[0:1], v[4:5], v[0:1]
	v_pk_mul_f32 v[2:3], v[6:7], v[2:3]
	v_exp_f32_e32 v206, v206
	v_exp_f32_e32 v207, v207
	v_exp_f32_e32 v208, v208
	v_exp_f32_e32 v209, v209
	v_pk_mul_f32 v[8:9], v[12:13], v[8:9]
	v_pk_mul_f32 v[10:11], v[14:15], v[10:11]
	v_pk_add_f32 v[200:201], v[200:201], 1.0 op_sel_hi:[1,0]
	v_pk_add_f32 v[202:203], v[202:203], 1.0 op_sel_hi:[1,0]
	v_rcp_f32_e32 v200, v200
	v_rcp_f32_e32 v201, v201
	v_rcp_f32_e32 v202, v202
	v_rcp_f32_e32 v203, v203
	v_pk_add_f32 v[206:207], v[206:207], 1.0 op_sel_hi:[1,0]
	v_pk_add_f32 v[208:209], v[208:209], 1.0 op_sel_hi:[1,0]
	v_rcp_f32_e32 v206, v206
	v_rcp_f32_e32 v207, v207
	v_rcp_f32_e32 v208, v208
	v_rcp_f32_e32 v209, v209
	v_pk_mul_f32 v[0:1], v[200:201], v[0:1]
	v_pk_mul_f32 v[2:3], v[202:203], v[2:3]
	v_pk_mul_f32 v[8:9], v[206:207], v[8:9]
	v_pk_mul_f32 v[10:11], v[208:209], v[10:11]
	v_cvt_pk_bf16_f32 v12, v8, v9
	v_cvt_pk_bf16_f32 v13, v10, v11
	v_cvt_pk_bf16_f32 v14, v0, v1
	v_cvt_pk_bf16_f32 v15, v2, v3
	v_add_u32_e32 v4, 0xb0, v156
	v_mad_i64_i32 v[4:5], s[26:27], v4, s56, v[112:113]
	v_lshl_add_u64 v[4:5], v[4:5], 0, v[114:115]
	s_andn2_b64 vcc, exec, s[4:5]
	s_mov_b64 s[4:5], -1
	global_store_dwordx4 v[4:5], v[12:15], off
	s_cbranch_vccnz .LBB0_794
	s_andn2_b64 vcc, exec, s[6:7]
	s_cbranch_vccnz .LBB0_793
	s_barrier
	s_branch .LBB0_793
